# NA attention loop: relative-position bias LDS reads made unconditional (masked lanes are overwritten by -inf afterwards), zero-inits dropped
# speedup vs baseline: 1.0058x; 1.0058x over previous
; DI int crow(int reg, int h) { return (reg & 3) + 8 * (reg >> 2) + 4 * h; }
; template <int DQK, bool NA>
; DI void attn_unit(const bf16_t* __restrict__ Qb, int ldq, const bf16_t* __restrict__ Kb, int ldk, const bf16_t* __restrict__ Vt,
;                   bf16_t* __restrict__ Ob, int ldo, int u, float sc, const float* __restrict__ rpb_h, char* smem) {
;     ...
;       if (NA) {
;         const int brow = (kt - rq + 7) * 31;
; #pragma unroll
;         for (int q = 0; q < 16; ++q) {
;           int kc0 = crow(q, h), kc1 = 32 + kc0;
;           bool v0 = (kc0 >= cs) && (kc0 < cs + 16), v1 = (kc1 >= cs) && (kc1 < cs + 16);
;           float b0 = v0 ? sBias[brow + kc0 - cq + 15] : 0.f;
;           float b1 = v1 ? sBias[brow + kc1 - cq + 15] : 0.f;
;           s0[q] = v0 ? (s0[q] * sc + b0) : -INFINITY;
;           s1[q] = v1 ? (s1[q] * sc + b1) : -INFINITY;
;         }
.LBB0_301:
	s_or_b64 exec, exec, vcc
	ds_read_b32 v142, v141 offset:132
	ds_read_b32 v143, v141 offset:8
	ds_read_b32 v144, v141 offset:136
	ds_read_b32 v145, v141 offset:12
	ds_read_b32 v146, v141 offset:140
	ds_read_b32 v147, v141 offset:32
	ds_read_b32 v148, v141 offset:160
	ds_read_b32 v149, v141 offset:36
	ds_read_b32 v150, v141 offset:164
	ds_read_b32 v151, v141 offset:40
	ds_read_b32 v152, v141 offset:168
	ds_read_b32 v153, v141 offset:44
	ds_read_b32 v154, v141 offset:172
	ds_read_b32 v14, v141 offset:64
	ds_read_b32 v155, v141 offset:192
	ds_read_b32 v15, v141 offset:68
	ds_read_b32 v156, v141 offset:196
	ds_read_b32 v10, v141 offset:72
	ds_read_b32 v12, v141 offset:200
	ds_read_b32 v11, v141 offset:76
	ds_read_b32 v13, v141 offset:204
	ds_read_b32 v6, v141 offset:96
	ds_read_b32 v8, v141 offset:224
	ds_read_b32 v7, v141 offset:100
	ds_read_b32 v9, v141 offset:228
	ds_read_b32 v2, v141 offset:104
	v_mov_b32_e32 v157, 0
	v_mov_b32_e32 v4, 0
	s_and_saveexec_b64 vcc, s[82:83]
	s_cbranch_execz .LBB0_365
	ds_read_b32 v4, v141 offset:232
	s_or_b64 exec, exec, vcc
	s_and_saveexec_b64 vcc, s[80:81]
	s_cbranch_execnz .LBB0_366
